# plus NA window mask/bias: batched LDS table lookups with v_cndmask instead of 32 exec-masked single lookups
# speedup vs baseline: 1.0067x; 1.0067x over previous
.LBB2_363:
	s_and_b32 s14, s16, 1
	s_add_i32 s4, s24, s16
	v_cmp_ge_u32_e32 vcc, s4, v165
	v_cmp_lt_u32_e64 s[4:5], s4, v187
	s_and_b64 s[4:5], vcc, s[4:5]
	s_and_saveexec_b64 s[36:37], s[4:5]
	s_cbranch_execz .LBB2_433
	s_lshl_b32 s15, s14, 14
	s_add_i32 s4, s15, 0
	v_add3_u32 v0, s4, v192, v191
	ds_read_b128 v[66:69], v0 offset:32768
	ds_read_b128 v[70:73], v0 offset:40960
	v_add3_u32 v0, s4, v193, v191
	ds_read_b128 v[238:241], v0 offset:32768
	ds_read_b128 v[242:245], v0 offset:40960
	v_add3_u32 v0, s4, v194, v191
	s_waitcnt lgkmcnt(0)
	v_mfma_f32_32x32x16_bf16 v[82:97], v[66:69], v[110:113], 0
	v_mfma_f32_32x32x16_bf16 v[66:81], v[70:73], v[110:113], 0
	v_mfma_f32_32x32x16_bf16 v[82:97], v[238:241], v[114:117], v[82:97]
	v_mfma_f32_32x32x16_bf16 v[66:81], v[242:245], v[114:117], v[66:81]
	ds_read_b128 v[238:241], v0 offset:32768
	ds_read_b128 v[242:245], v0 offset:40960
	v_add3_u32 v0, s4, v195, v191
	s_waitcnt lgkmcnt(0)
	v_mfma_f32_32x32x16_bf16 v[82:97], v[238:241], v[122:125], v[82:97]
	v_mfma_f32_32x32x16_bf16 v[66:81], v[242:245], v[122:125], v[66:81]
	ds_read_b128 v[238:241], v0 offset:32768
	ds_read_b128 v[242:245], v0 offset:40960
	v_add3_u32 v0, s4, v196, v191
	s_waitcnt lgkmcnt(0)
	v_mfma_f32_32x32x16_bf16 v[82:97], v[238:241], v[126:129], v[82:97]
	v_mfma_f32_32x32x16_bf16 v[66:81], v[242:245], v[126:129], v[66:81]
	ds_read_b128 v[238:241], v0 offset:32768
	ds_read_b128 v[242:245], v0 offset:40960
	v_add3_u32 v0, s4, v197, v191
	s_waitcnt lgkmcnt(0)
	v_mfma_f32_32x32x16_bf16 v[82:97], v[238:241], v[130:133], v[82:97]
	v_mfma_f32_32x32x16_bf16 v[66:81], v[242:245], v[130:133], v[66:81]
	ds_read_b128 v[238:241], v0 offset:32768
	ds_read_b128 v[242:245], v0 offset:40960
	v_add3_u32 v0, s4, v198, v191
	s_waitcnt lgkmcnt(0)
	v_mfma_f32_32x32x16_bf16 v[82:97], v[238:241], v[134:137], v[82:97]
	v_mfma_f32_32x32x16_bf16 v[66:81], v[242:245], v[134:137], v[66:81]
	ds_read_b128 v[238:241], v0 offset:32768
	ds_read_b128 v[242:245], v0 offset:40960
	v_add3_u32 v0, s4, v199, v191
	s_waitcnt lgkmcnt(0)
	v_mfma_f32_32x32x16_bf16 v[82:97], v[238:241], v[138:141], v[82:97]
	v_mfma_f32_32x32x16_bf16 v[66:81], v[242:245], v[138:141], v[66:81]
	ds_read_b128 v[238:241], v0 offset:32768
	ds_read_b128 v[242:245], v0 offset:40960
	v_add_u32_e32 v0, s16, v201
	v_max_i32_e32 v0, -7, v0
	v_add_u32_e32 v0, 7, v0
	v_min_u32_e32 v0, 14, v0
	s_waitcnt lgkmcnt(0)
	v_mfma_f32_32x32x16_bf16 v[82:97], v[238:241], v[142:145], v[82:97]
	v_mul_u32_u24_e32 v239, 31, v0
	v_mov_b32_e32 v0, 0xf149f2ca
	v_mov_b32_e32 v238, 0xf149f2ca
	v_mfma_f32_32x32x16_bf16 v[66:81], v[242:245], v[142:145], v[66:81]
	v_mov_b32_e32 v244, 0xf149f2ca
	v_lshl_add_u32 v156, v239, 2, v204
	ds_read_b32 v156, v156 offset:60
	v_lshl_add_u32 v157, v239, 2, v205
	ds_read_b32 v157, v157 offset:60
	v_lshl_add_u32 v158, v239, 2, v206
	ds_read_b32 v158, v158 offset:60
	v_lshl_add_u32 v159, v239, 2, v207
	ds_read_b32 v159, v159 offset:60
	v_lshl_add_u32 v240, v239, 2, v208
	ds_read_b32 v240, v240 offset:60
	v_lshl_add_u32 v241, v239, 2, v209
	ds_read_b32 v241, v241 offset:60
	v_lshl_add_u32 v242, v239, 2, v210
	ds_read_b32 v242, v242 offset:60
	v_lshl_add_u32 v243, v239, 2, v211
	ds_read_b32 v243, v243 offset:60
	s_waitcnt lgkmcnt(0)
	v_add_f32_e32 v156, v82, v156
	v_cndmask_b32_e64 v238, v244, v156, s[38:39]
	v_add_f32_e32 v157, v66, v157
	v_cndmask_b32_e64 v0, v244, v157, s[40:41]
	v_add_f32_e32 v158, v83, v158
	v_cndmask_b32_e64 v82, v244, v158, s[42:43]
	v_add_f32_e32 v159, v67, v159
	v_cndmask_b32_e64 v66, v244, v159, s[44:45]
	v_add_f32_e32 v240, v84, v240
	v_cndmask_b32_e64 v83, v244, v240, s[46:47]
	v_add_f32_e32 v241, v68, v241
	v_cndmask_b32_e64 v67, v244, v241, s[48:49]
	v_add_f32_e32 v242, v85, v242
	v_cndmask_b32_e64 v84, v244, v242, s[50:51]
	v_add_f32_e32 v243, v69, v243
	v_cndmask_b32_e64 v68, v244, v243, s[52:53]
	v_lshl_add_u32 v156, v239, 2, v212
	ds_read_b32 v156, v156 offset:60
	v_lshl_add_u32 v157, v239, 2, v213
	ds_read_b32 v157, v157 offset:60
	v_lshl_add_u32 v158, v239, 2, v214
	ds_read_b32 v158, v158 offset:60
	v_lshl_add_u32 v159, v239, 2, v215
	ds_read_b32 v159, v159 offset:60
	v_lshl_add_u32 v240, v239, 2, v216
	ds_read_b32 v240, v240 offset:60
	v_lshl_add_u32 v241, v239, 2, v217
	ds_read_b32 v241, v241 offset:60
	v_lshl_add_u32 v242, v239, 2, v218
	ds_read_b32 v242, v242 offset:60
	v_lshl_add_u32 v243, v239, 2, v219
	ds_read_b32 v243, v243 offset:60
	s_waitcnt lgkmcnt(0)
	v_add_f32_e32 v156, v86, v156
	v_cndmask_b32_e64 v85, v244, v156, s[54:55]
	v_add_f32_e32 v157, v70, v157
	v_cndmask_b32_e64 v69, v244, v157, s[56:57]
	v_add_f32_e32 v158, v87, v158
	v_cndmask_b32_e64 v86, v244, v158, s[58:59]
	v_add_f32_e32 v159, v71, v159
	v_cndmask_b32_e64 v70, v244, v159, s[60:61]
	v_add_f32_e32 v240, v88, v240
	v_cndmask_b32_e64 v87, v244, v240, s[62:63]
	v_add_f32_e32 v241, v72, v241
	v_cndmask_b32_e64 v71, v244, v241, s[64:65]
	v_add_f32_e32 v242, v89, v242
	v_cndmask_b32_e64 v88, v244, v242, s[66:67]
	v_add_f32_e32 v243, v73, v243
	v_cndmask_b32_e64 v72, v244, v243, s[68:69]
	v_lshl_add_u32 v156, v239, 2, v220
	ds_read_b32 v156, v156 offset:60
	v_lshl_add_u32 v157, v239, 2, v221
	ds_read_b32 v157, v157 offset:60
	v_lshl_add_u32 v158, v239, 2, v222
	ds_read_b32 v158, v158 offset:60
	v_lshl_add_u32 v159, v239, 2, v223
	ds_read_b32 v159, v159 offset:60
	v_lshl_add_u32 v240, v239, 2, v224
	ds_read_b32 v240, v240 offset:60
	v_lshl_add_u32 v241, v239, 2, v225
	ds_read_b32 v241, v241 offset:60
	v_lshl_add_u32 v242, v239, 2, v226
	ds_read_b32 v242, v242 offset:60
	v_lshl_add_u32 v243, v239, 2, v227
	ds_read_b32 v243, v243 offset:60
	s_waitcnt lgkmcnt(0)
	v_add_f32_e32 v156, v90, v156
	v_cndmask_b32_e64 v89, v244, v156, s[70:71]
	v_add_f32_e32 v157, v74, v157
	v_cndmask_b32_e64 v73, v244, v157, s[72:73]
	v_add_f32_e32 v158, v91, v158
	v_cndmask_b32_e64 v90, v244, v158, s[74:75]
	v_add_f32_e32 v159, v75, v159
	v_cndmask_b32_e64 v74, v244, v159, s[76:77]
	v_add_f32_e32 v240, v92, v240
	v_cndmask_b32_e64 v91, v244, v240, s[78:79]
	v_add_f32_e32 v241, v76, v241
	v_cndmask_b32_e64 v75, v244, v241, s[80:81]
	v_add_f32_e32 v242, v93, v242
	v_cndmask_b32_e64 v92, v244, v242, s[82:83]
	v_add_f32_e32 v243, v77, v243
	v_cndmask_b32_e64 v76, v244, v243, s[84:85]
	v_lshl_add_u32 v156, v239, 2, v228
	ds_read_b32 v156, v156 offset:60
	v_lshl_add_u32 v157, v239, 2, v229
	ds_read_b32 v157, v157 offset:60
	v_lshl_add_u32 v158, v239, 2, v230
	ds_read_b32 v158, v158 offset:60
	v_lshl_add_u32 v159, v239, 2, v231
	ds_read_b32 v159, v159 offset:60
	v_lshl_add_u32 v240, v239, 2, v232
	ds_read_b32 v240, v240 offset:60
	v_lshl_add_u32 v241, v239, 2, v233
	ds_read_b32 v241, v241 offset:60
	v_lshl_add_u32 v242, v239, 2, v234
	ds_read_b32 v242, v242 offset:60
	v_lshl_add_u32 v243, v239, 2, v235
	ds_read_b32 v243, v243 offset:60
	s_waitcnt lgkmcnt(0)
	v_add_f32_e32 v156, v94, v156
	v_cndmask_b32_e64 v93, v244, v156, s[86:87]
	v_add_f32_e32 v157, v78, v157
	v_cndmask_b32_e64 v77, v244, v157, s[88:89]
	v_add_f32_e32 v158, v95, v158
	v_cndmask_b32_e64 v94, v244, v158, s[90:91]
	v_add_f32_e32 v159, v79, v159
	v_cndmask_b32_e64 v78, v244, v159, s[92:93]
	v_add_f32_e32 v240, v96, v240
	v_cndmask_b32_e64 v95, v244, v240, s[94:95]
	v_add_f32_e32 v241, v80, v241
	v_cndmask_b32_e64 v79, v244, v241, s[96:97]
	v_add_f32_e32 v242, v97, v242
	v_cndmask_b32_e64 v96, v244, v242, s[98:99]
	v_add_f32_e32 v243, v81, v243
	v_cndmask_b32_e64 v80, v244, v243, s[6:7]
	v_max_f32_e32 v81, v82, v82
	v_max_f32_e32 v97, v238, v238
	v_max_f32_e32 v81, v97, v81
	v_max3_f32 v81, v81, v83, v84
	v_max3_f32 v81, v81, v85, v86
	v_max3_f32 v81, v81, v87, v88
	v_max3_f32 v81, v81, v89, v90
	v_max3_f32 v81, v81, v91, v92
	v_max3_f32 v81, v81, v93, v94
	v_max3_f32 v81, v81, v95, v96
	v_max3_f32 v81, v81, v0, v66
	v_max3_f32 v81, v81, v67, v68
	v_max3_f32 v81, v81, v69, v70
	v_max3_f32 v81, v81, v71, v72
	v_max3_f32 v81, v81, v73, v74
	v_max3_f32 v81, v81, v75, v76
	v_max3_f32 v81, v81, v77, v78
	v_max3_f32 v81, v81, v79, v80
	v_mov_b32_e32 v97, v81
	s_nop 1
	v_permlane32_swap_b32_e32 v81, v97
	v_max_f32_e32 v97, v97, v97
	v_max_f32_e32 v81, v81, v81
	v_max_f32_e32 v81, v81, v97
	v_sub_f32_e32 v97, v81, v236
	s_mov_b32 s4, 0x42b504f3
	v_cmp_ge_f32_e32 vcc, s4, v97
	v_max_f32_e32 v97, v236, v236
	v_max_f32_e32 v97, v97, v81
	v_sub_f32_e32 v81, v236, v97
	v_mul_f32_e32 v81, 0x3e0293ee, v81
	v_exp_f32_e32 v81, v81
	s_cmp_eq_u64 vcc, exec
	s_cselect_b64 s[4:5], -1, 0
	v_cndmask_b32_e64 v81, v81, 1.0, s[4:5]
	v_cmp_gt_f32_e32 vcc, 1.0, v81
	s_cbranch_vccz .LBB2_432
	s_and_saveexec_b64 vcc, s[0:1]
	ds_write_b32 v203, v81 offset:128
	s_or_b64 exec, exec, vcc
	s_waitcnt lgkmcnt(0)
	ds_read_b128 v[240:243], v200 offset:224
	ds_read_b128 v[244:247], v200 offset:192
	ds_read_b128 v[248:251], v200 offset:160
	ds_read_b128 v[156:159], v200 offset:128
	s_waitcnt lgkmcnt(0)
	v_pk_mul_f32 v[64:65], v[64:65], v[242:243]
	v_pk_mul_f32 v[60:61], v[60:61], v[246:247]
	v_pk_mul_f32 v[56:57], v[56:57], v[250:251]
	v_pk_mul_f32 v[52:53], v[52:53], v[158:159]
	v_pk_mul_f32 v[62:63], v[62:63], v[240:241]
	v_pk_mul_f32 v[58:59], v[58:59], v[244:245]
	v_pk_mul_f32 v[54:55], v[54:55], v[248:249]
	v_pk_mul_f32 v[50:51], v[50:51], v[156:157]
	v_pk_mul_f32 v[48:49], v[48:49], v[242:243]
	v_pk_mul_f32 v[44:45], v[44:45], v[246:247]
	v_pk_mul_f32 v[40:41], v[40:41], v[250:251]
	v_pk_mul_f32 v[36:37], v[36:37], v[158:159]
	v_pk_mul_f32 v[46:47], v[46:47], v[240:241]
	v_pk_mul_f32 v[42:43], v[42:43], v[244:245]
	v_pk_mul_f32 v[38:39], v[38:39], v[248:249]
	v_pk_mul_f32 v[34:35], v[34:35], v[156:157]
	v_pk_mul_f32 v[32:33], v[32:33], v[242:243]
	v_pk_mul_f32 v[28:29], v[28:29], v[246:247]
	v_pk_mul_f32 v[24:25], v[24:25], v[250:251]
	v_pk_mul_f32 v[20:21], v[20:21], v[158:159]
	v_pk_mul_f32 v[30:31], v[30:31], v[240:241]
	v_pk_mul_f32 v[26:27], v[26:27], v[244:245]
	v_pk_mul_f32 v[22:23], v[22:23], v[248:249]
	v_pk_mul_f32 v[18:19], v[18:19], v[156:157]
	v_pk_mul_f32 v[16:17], v[16:17], v[242:243]
	v_pk_mul_f32 v[12:13], v[12:13], v[246:247]
	v_pk_mul_f32 v[8:9], v[8:9], v[250:251]
	v_pk_mul_f32 v[4:5], v[4:5], v[158:159]
	v_pk_mul_f32 v[14:15], v[14:15], v[240:241]
	v_pk_mul_f32 v[10:11], v[10:11], v[244:245]
	v_pk_mul_f32 v[6:7], v[6:7], v[248:249]
	v_pk_mul_f32 v[2:3], v[2:3], v[156:157]
